# grid barrier: non-leader workgroups issue the L1 invalidate before polling instead of after (nothing is loaded through L1 in between)
# speedup vs baseline: 1.0084x; 1.0084x over previous
.LBB0_132:
	s_or_b64 exec, exec, s[12:13]
	v_cvt_f32_u32_e32 v4, v2
	s_waitcnt vmcnt(0)
	v_readfirstlane_b32 s2, v3
	v_sub_u32_e32 v3, 0, v2
	v_rcp_iflag_f32_e32 v4, v4
	v_add_u32_e32 v5, s2, v1
	v_mul_f32_e32 v4, 0x4f7ffffe, v4
	v_cvt_u32_f32_e32 v4, v4
	v_mul_lo_u32 v1, v3, v4
	v_mul_hi_u32 v1, v4, v1
	v_add_u32_e32 v1, v4, v1
	v_mul_hi_u32 v1, v5, v1
	v_mul_lo_u32 v3, v1, v2
	v_sub_u32_e32 v3, v5, v3
	v_add_u32_e32 v4, 1, v1
	v_cmp_ge_u32_e32 vcc, v3, v2
	s_nop 1
	v_cndmask_b32_e32 v1, v1, v4, vcc
	v_sub_u32_e32 v4, v3, v2
	v_cndmask_b32_e32 v3, v3, v4, vcc
	v_add_u32_e32 v4, 1, v1
	v_cmp_ge_u32_e32 vcc, v3, v2
	v_add_u32_e32 v3, 1, v5
	s_nop 0
	v_cndmask_b32_e32 v1, v1, v4, vcc
	v_mul_lo_u32 v4, v2, v1
	v_add_u32_e32 v2, v4, v2
	v_cmp_ne_u32_e32 vcc, v3, v2
	s_and_saveexec_b64 s[2:3], vcc
	s_xor_b64 s[10:11], exec, s[2:3]
	s_cbranch_execz .LBB0_146
	s_waitcnt lgkmcnt(0)
	v_mov_b32_e32 v0, 0x2000
	buffer_inv sc1
	global_load_dword v0, v0, s[8:9] offset:1024 sc1
	s_add_u32 s16, s8, 0x2400
	s_addc_u32 s17, s9, 0
	s_waitcnt vmcnt(0)
	v_cmp_eq_u32_e32 vcc, v0, v1
	s_and_saveexec_b64 s[12:13], vcc
	s_cbranch_execz .LBB0_145
	s_add_u32 s14, s6, 0x10200
	s_addc_u32 s15, s7, 0
	s_mov_b32 s2, 1
	s_mov_b64 s[18:19], 0
	v_mov_b32_e32 v0, 0
	s_branch .LBB0_136

.LBB0_145:
	s_or_b64 exec, exec, s[12:13]
	s_waitcnt vmcnt(0)
	s_waitcnt vmcnt(0)

.LBB0_209:
	s_or_b64 exec, exec, s[12:13]
	v_cvt_f32_u32_e32 v5, v3
	s_waitcnt vmcnt(0)
	v_readfirstlane_b32 s10, v4
	v_sub_u32_e32 v4, 0, v3
	v_rcp_iflag_f32_e32 v5, v5
	v_add_u32_e32 v6, s10, v1
	v_mul_f32_e32 v5, 0x4f7ffffe, v5
	v_cvt_u32_f32_e32 v5, v5
	v_mul_lo_u32 v1, v4, v5
	v_mul_hi_u32 v1, v5, v1
	v_add_u32_e32 v1, v5, v1
	v_mul_hi_u32 v1, v6, v1
	v_mul_lo_u32 v4, v1, v3
	v_sub_u32_e32 v4, v6, v4
	v_add_u32_e32 v5, 1, v1
	v_cmp_ge_u32_e32 vcc, v4, v3
	s_nop 1
	v_cndmask_b32_e32 v1, v1, v5, vcc
	v_sub_u32_e32 v5, v4, v3
	v_cndmask_b32_e32 v4, v4, v5, vcc
	v_add_u32_e32 v5, 1, v1
	v_cmp_ge_u32_e32 vcc, v4, v3
	v_add_u32_e32 v4, 1, v6
	s_nop 0
	v_cndmask_b32_e32 v1, v1, v5, vcc
	v_mul_lo_u32 v5, v3, v1
	v_add_u32_e32 v3, v5, v3
	v_cmp_ne_u32_e32 vcc, v4, v3
	s_and_saveexec_b64 s[10:11], vcc
	s_xor_b64 s[10:11], exec, s[10:11]
	s_cbranch_execz .LBB0_223
	s_waitcnt lgkmcnt(0)
	v_mov_b32_e32 v2, 0x2000
	buffer_inv sc1
	global_load_dword v2, v2, s[8:9] offset:1024 sc1
	s_add_u32 s16, s8, 0x2400
	s_addc_u32 s17, s9, 0
	s_waitcnt vmcnt(0)
	v_cmp_eq_u32_e32 vcc, v2, v1
	s_and_saveexec_b64 s[12:13], vcc
	s_cbranch_execz .LBB0_222
	s_add_u32 s14, s6, 0x10200
	s_addc_u32 s15, s7, 0
	s_mov_b32 s18, 1
	s_mov_b64 s[20:21], 0
	s_branch .LBB0_213

.LBB0_1286:
	s_or_b64 exec, exec, s[12:13]
	v_cvt_f32_u32_e32 v5, v3
	s_waitcnt vmcnt(0)
	v_readfirstlane_b32 s10, v4
	v_sub_u32_e32 v4, 0, v3
	v_rcp_iflag_f32_e32 v5, v5
	v_add_u32_e32 v6, s10, v1
	v_mul_f32_e32 v5, 0x4f7ffffe, v5
	v_cvt_u32_f32_e32 v5, v5
	v_mul_lo_u32 v1, v4, v5
	v_mul_hi_u32 v1, v5, v1
	v_add_u32_e32 v1, v5, v1
	v_mul_hi_u32 v1, v6, v1
	v_mul_lo_u32 v4, v1, v3
	v_sub_u32_e32 v4, v6, v4
	v_add_u32_e32 v5, 1, v1
	v_cmp_ge_u32_e32 vcc, v4, v3
	s_nop 1
	v_cndmask_b32_e32 v1, v1, v5, vcc
	v_sub_u32_e32 v5, v4, v3
	v_cndmask_b32_e32 v4, v4, v5, vcc
	v_add_u32_e32 v5, 1, v1
	v_cmp_ge_u32_e32 vcc, v4, v3
	v_add_u32_e32 v4, 1, v6
	s_nop 0
	v_cndmask_b32_e32 v1, v1, v5, vcc
	v_mul_lo_u32 v5, v3, v1
	v_add_u32_e32 v3, v5, v3
	v_cmp_ne_u32_e32 vcc, v4, v3
	s_and_saveexec_b64 s[10:11], vcc
	s_xor_b64 s[10:11], exec, s[10:11]
	s_mov_b32 s54, 0x8000
	s_cbranch_execz .LBB0_1300
	s_waitcnt lgkmcnt(0)
	v_mov_b32_e32 v2, 0x2000
	buffer_inv sc1
	global_load_dword v2, v2, s[8:9] offset:1024 sc1
	s_add_u32 s16, s8, 0x2400
	s_addc_u32 s17, s9, 0
	s_waitcnt vmcnt(0)
	v_cmp_eq_u32_e32 vcc, v2, v1
	s_and_saveexec_b64 s[12:13], vcc
	s_cbranch_execz .LBB0_1299
	s_add_u32 s14, s6, 0x10200
	s_addc_u32 s15, s7, 0
	s_mov_b32 s38, 1
	s_mov_b64 s[18:19], 0
	s_branch .LBB0_1290

.LBB0_1400:
	s_or_b64 exec, exec, s[12:13]
	v_cvt_f32_u32_e32 v5, v3
	s_waitcnt vmcnt(0)
	v_readfirstlane_b32 s10, v4
	v_sub_u32_e32 v4, 0, v3
	v_rcp_iflag_f32_e32 v5, v5
	v_add_u32_e32 v6, s10, v1
	v_mul_f32_e32 v5, 0x4f7ffffe, v5
	v_cvt_u32_f32_e32 v5, v5
	v_mul_lo_u32 v1, v4, v5
	v_mul_hi_u32 v1, v5, v1
	v_add_u32_e32 v1, v5, v1
	v_mul_hi_u32 v1, v6, v1
	v_mul_lo_u32 v4, v1, v3
	v_sub_u32_e32 v4, v6, v4
	v_add_u32_e32 v5, 1, v1
	v_cmp_ge_u32_e32 vcc, v4, v3
	s_nop 1
	v_cndmask_b32_e32 v1, v1, v5, vcc
	v_sub_u32_e32 v5, v4, v3
	v_cndmask_b32_e32 v4, v4, v5, vcc
	v_add_u32_e32 v5, 1, v1
	v_cmp_ge_u32_e32 vcc, v4, v3
	v_add_u32_e32 v4, 1, v6
	s_nop 0
	v_cndmask_b32_e32 v1, v1, v5, vcc
	v_mul_lo_u32 v5, v3, v1
	v_add_u32_e32 v3, v5, v3
	v_cmp_ne_u32_e32 vcc, v4, v3
	s_and_saveexec_b64 s[10:11], vcc
	s_xor_b64 s[10:11], exec, s[10:11]
	s_cbranch_execz .LBB0_1414
	s_waitcnt lgkmcnt(0)
	v_mov_b32_e32 v2, 0x2000
	buffer_inv sc1
	global_load_dword v2, v2, s[8:9] offset:1024 sc1
	s_add_u32 s16, s8, 0x2400
	s_addc_u32 s17, s9, 0
	s_waitcnt vmcnt(0)
	v_cmp_eq_u32_e32 vcc, v2, v1
	s_and_saveexec_b64 s[12:13], vcc
	s_cbranch_execz .LBB0_1413
	s_add_u32 s14, s6, 0x10200
	s_addc_u32 s15, s7, 0
	s_mov_b32 s38, 1
	s_mov_b64 s[18:19], 0
	s_branch .LBB0_1404
